# WY producer: right-hand sides of waves 4-7 with LDS row addresses folded into ds_read2 offset immediates and packed multiplies (85 instructions instead of 162)
# baseline (speedup 1.0000x reference)
; __device__ __forceinline__ int wy_producer_task(const Ctx& c, int l, int tk, WyPre& P, unsigned* head) {
;     ...
;     else {
; #pragma unroll
;         for (int t = 0; t < 16; ++t) { const int i = 4 * t + q4; own[t] = BE[i] * __expf(GC[i]) * KF[i * 65 + 16 * (wid - 4) + cc]; } }
.LBB0_1043:
	v_lshlrev_b32_e32 v38, 2, v0
	v_add_u32_e32 v40, 0x11b00, v38
	v_mov_b32_e32 v54, 0x3fb8aa3b
	ds_read2_b32 v[22:23], v40 offset0:0 offset1:4
	ds_read2_b32 v[24:25], v40 offset0:8 offset1:12
	ds_read2_b32 v[26:27], v40 offset0:16 offset1:20
	ds_read2_b32 v[28:29], v40 offset0:24 offset1:28
	ds_read2_b32 v[30:31], v40 offset0:32 offset1:36
	ds_read2_b32 v[32:33], v40 offset0:40 offset1:44
	ds_read2_b32 v[34:35], v40 offset0:48 offset1:52
	ds_read2_b32 v[36:37], v40 offset0:56 offset1:60
	ds_read2_b32 v[56:57], v40 offset0:64 offset1:68
	ds_read2_b32 v[58:59], v40 offset0:72 offset1:76
	ds_read2_b32 v[60:61], v40 offset0:80 offset1:84
	ds_read2_b32 v[62:63], v40 offset0:88 offset1:92
	ds_read2_b32 v[64:65], v40 offset0:96 offset1:100
	ds_read2_b32 v[66:67], v40 offset0:104 offset1:108
	ds_read2_b32 v[68:69], v40 offset0:112 offset1:116
	s_waitcnt lgkmcnt(7)
	v_pk_mul_f32 v[22:23], v[22:23], v[54:55] op_sel_hi:[1,0]
	v_pk_mul_f32 v[24:25], v[24:25], v[54:55] op_sel_hi:[1,0]
	v_pk_mul_f32 v[26:27], v[26:27], v[54:55] op_sel_hi:[1,0]
	v_pk_mul_f32 v[28:29], v[28:29], v[54:55] op_sel_hi:[1,0]
	v_pk_mul_f32 v[30:31], v[30:31], v[54:55] op_sel_hi:[1,0]
	v_pk_mul_f32 v[32:33], v[32:33], v[54:55] op_sel_hi:[1,0]
	v_pk_mul_f32 v[34:35], v[34:35], v[54:55] op_sel_hi:[1,0]
	v_pk_mul_f32 v[36:37], v[36:37], v[54:55] op_sel_hi:[1,0]
	ds_read2_b32 v[70:71], v40 offset0:120 offset1:124
	ds_read_b32 v18, v3 offset:768
	ds_read_b32 v19, v3 offset:1808
	ds_read_b32 v16, v3 offset:2848
	ds_read_b32 v17, v3 offset:3888
	ds_read_b32 v14, v3 offset:4928
	ds_read_b32 v15, v3 offset:5968
	ds_read_b32 v12, v3 offset:7008
	v_exp_f32_e32 v22, v22
	v_exp_f32_e32 v23, v23
	v_exp_f32_e32 v24, v24
	v_exp_f32_e32 v25, v25
	v_exp_f32_e32 v26, v26
	v_exp_f32_e32 v27, v27
	v_exp_f32_e32 v28, v28
	v_exp_f32_e32 v29, v29
	v_exp_f32_e32 v30, v30
	v_exp_f32_e32 v31, v31
	v_exp_f32_e32 v32, v32
	v_exp_f32_e32 v33, v33
	v_exp_f32_e32 v34, v34
	v_exp_f32_e32 v35, v35
	v_exp_f32_e32 v36, v36
	v_exp_f32_e32 v37, v37
	s_waitcnt lgkmcnt(7)
	v_pk_mul_f32 v[56:57], v[56:57], v[22:23]
	v_pk_mul_f32 v[58:59], v[58:59], v[24:25]
	v_pk_mul_f32 v[60:61], v[60:61], v[26:27]
	v_pk_mul_f32 v[62:63], v[62:63], v[28:29]
	v_pk_mul_f32 v[64:65], v[64:65], v[30:31]
	v_pk_mul_f32 v[66:67], v[66:67], v[32:33]
	v_pk_mul_f32 v[68:69], v[68:69], v[34:35]
	v_pk_mul_f32 v[70:71], v[70:71], v[36:37]
	ds_read_b32 v13, v3 offset:8048
	ds_read_b32 v10, v3 offset:9088
	ds_read_b32 v11, v3 offset:10128
	ds_read_b32 v8, v3 offset:11168
	ds_read_b32 v9, v3 offset:12208
	ds_read_b32 v6, v3 offset:13248
	ds_read_b32 v7, v3 offset:14288
	s_waitcnt lgkmcnt(12)
	ds_read_b32 v4, v3 offset:15328
	v_pk_mul_f32 v[18:19], v[18:19], v[56:57]
	s_waitcnt lgkmcnt(11)
	ds_read_b32 v5, v3 offset:16368
	v_pk_mul_f32 v[16:17], v[16:17], v[58:59]
	s_waitcnt lgkmcnt(10)
	v_pk_mul_f32 v[14:15], v[14:15], v[60:61]
	s_waitcnt lgkmcnt(8)
	v_pk_mul_f32 v[12:13], v[12:13], v[62:63]
	s_waitcnt lgkmcnt(6)
	v_pk_mul_f32 v[10:11], v[10:11], v[64:65]
	s_waitcnt lgkmcnt(4)
	v_pk_mul_f32 v[8:9], v[8:9], v[66:67]
	s_waitcnt lgkmcnt(2)
	v_pk_mul_f32 v[6:7], v[6:7], v[68:69]
	s_waitcnt lgkmcnt(0)
	v_pk_mul_f32 v[4:5], v[4:5], v[70:71]
	s_cbranch_execnz .LBB0_1042
